# L1 warm-up sweep before the serialized ushort-load loops of rwkv_lora / rwkv_post; gla_inter o-MFMA LDS reads software-pipelined
# speedup vs baseline: 1.0360x; 1.0086x over previous
.LBB0_442:
	s_add_i32 s16, s18, -1
	s_and_b64 s[14:15], s[2:3], exec
	s_cselect_b32 s14, s16, s34
	s_add_i32 s14, s14, s13
	s_ashr_i32 s15, s14, 31
	s_lshl_b64 s[14:15], s[14:15], 18
	v_lshl_add_u64 v[70:71], v[142:143], 0, s[14:15]
	v_lshl_add_u64 v[150:151], v[70:71], 0, v[140:141]
	v_lshl_add_u64 v[144:145], v[70:71], 0, v[134:135]
	v_lshl_add_u64 v[146:147], v[70:71], 0, v[136:137]
	v_lshl_add_u64 v[148:149], v[70:71], 0, v[138:139]
	global_load_ushort v184, v[150:151], off
	global_load_ushort v181, v[144:145], off
	global_load_ushort v180, v[144:145], off offset:32
	global_load_ushort v182, v[146:147], off
	global_load_ushort v179, v[146:147], off offset:32
	global_load_ushort v183, v[148:149], off
	global_load_ushort v178, v[148:149], off offset:32
	global_load_ushort v177, v[150:151], off offset:32
	s_add_i32 s18, s18, 1
	s_cmp_eq_u32 s19, -1
	ds_read_b128 v[186:189], v130 offset:33792
	ds_read_b128 v[190:193], v167
	ds_read_b128 v[194:197], v168
	ds_read_b128 v[198:201], v130 offset:33856
	ds_read_b128 v[202:205], v167 offset:64
	ds_read_b128 v[206:209], v168 offset:64
	ds_read_b128 v[210:213], v130 offset:33920
	ds_read_b128 v[214:217], v167 offset:128
	ds_read_b128 v[218:221], v168 offset:128
	ds_read_b128 v[234:237], v130 offset:33984
	ds_read_b128 v[238:241], v167 offset:192
	ds_read_b128 v[242:245], v168 offset:192
	s_waitcnt lgkmcnt(9)
	v_mfma_f32_16x16x32_bf16 v[74:77], v[186:189], v[190:193], 0
	v_mfma_f32_16x16x32_bf16 v[70:73], v[186:189], v[194:197], 0
	ds_read_b128 v[186:189], v130 offset:34048
	ds_read_b128 v[190:193], v167 offset:256
	ds_read_b128 v[194:197], v168 offset:256
	s_waitcnt lgkmcnt(9)
	v_mfma_f32_16x16x32_bf16 v[74:77], v[198:201], v[202:205], v[74:77]
	v_mfma_f32_16x16x32_bf16 v[70:73], v[198:201], v[206:209], v[70:73]
	ds_read_b128 v[198:201], v130 offset:34112
	ds_read_b128 v[202:205], v167 offset:320
	ds_read_b128 v[206:209], v168 offset:320
	s_waitcnt lgkmcnt(9)
	v_mfma_f32_16x16x32_bf16 v[74:77], v[210:213], v[214:217], v[74:77]
	v_mfma_f32_16x16x32_bf16 v[70:73], v[210:213], v[218:221], v[70:73]
	ds_read_b128 v[210:213], v130 offset:34176
	ds_read_b128 v[214:217], v167 offset:384
	ds_read_b128 v[218:221], v168 offset:384
	s_waitcnt lgkmcnt(9)
	v_mfma_f32_16x16x32_bf16 v[74:77], v[234:237], v[238:241], v[74:77]
	v_mfma_f32_16x16x32_bf16 v[70:73], v[234:237], v[242:245], v[70:73]
	s_waitcnt lgkmcnt(6)
	v_mfma_f32_16x16x32_bf16 v[74:77], v[186:189], v[190:193], v[74:77]
	v_mfma_f32_16x16x32_bf16 v[70:73], v[186:189], v[194:197], v[70:73]
	s_waitcnt lgkmcnt(3)
	v_mfma_f32_16x16x32_bf16 v[74:77], v[198:201], v[202:205], v[74:77]
	v_mfma_f32_16x16x32_bf16 v[70:73], v[198:201], v[206:209], v[70:73]
	s_waitcnt lgkmcnt(0)
	v_mfma_f32_16x16x32_bf16 v[74:77], v[210:213], v[214:217], v[74:77]
	v_mfma_f32_16x16x32_bf16 v[70:73], v[210:213], v[218:221], v[70:73]
	ds_read_b128 v[78:81], v130 offset:34240
	ds_read_b128 v[82:85], v167 offset:448
	ds_read_b128 v[86:89], v169
	s_waitcnt lgkmcnt(0)
	v_pk_mul_f32 v[96:97], v[40:41], v[88:89]
	v_mfma_f32_16x16x32_bf16 v[74:77], v[78:81], v[82:85], v[74:77]
	ds_read_b128 v[82:85], v168 offset:448
	v_pk_mul_f32 v[94:95], v[38:39], v[86:87]
	v_pk_mul_f32 v[40:41], v[64:65], v[88:89]
	s_waitcnt lgkmcnt(0)
	v_mfma_f32_16x16x32_bf16 v[70:73], v[78:81], v[82:85], v[70:73]
	v_mul_f32_e64 v84, v48, v88
	v_mul_f32_e64 v85, v49, v89
	v_pk_mul_f32 v[82:83], v[46:47], v[86:87]
	ds_read_b128 v[46:49], v169 offset:64
	v_pk_mul_f32 v[80:81], v[52:53], v[88:89]
	v_pk_mul_f32 v[78:79], v[50:51], v[86:87]
	v_pk_mul_f32 v[38:39], v[62:63], v[86:87]
	s_nop 0
	s_waitcnt vmcnt(0)
	v_lshlrev_b32_e32 v180, 16, v180
	v_lshlrev_b32_e32 v181, 16, v181
	v_lshlrev_b32_e32 v179, 16, v179
	v_lshlrev_b32_e32 v182, 16, v182
	v_lshlrev_b32_e32 v178, 16, v178
	v_lshlrev_b32_e32 v183, 16, v183
	v_lshlrev_b32_e32 v177, 16, v177
	v_lshlrev_b32_e32 v184, 16, v184
	v_add_f32_e32 v70, v70, v180
	s_waitcnt lgkmcnt(0)
	v_pk_mul_f32 v[52:53], v[44:45], v[48:49]
	v_pk_mul_f32 v[50:51], v[42:43], v[46:47]
	v_pk_mul_f32 v[92:93], v[56:57], v[48:49]
	v_pk_mul_f32 v[90:91], v[54:55], v[46:47]
	v_pk_mul_f32 v[88:89], v[60:61], v[48:49]
	v_pk_mul_f32 v[86:87], v[58:59], v[46:47]
	v_pk_mul_f32 v[44:45], v[68:69], v[48:49]
	v_pk_mul_f32 v[42:43], v[66:67], v[46:47]
	ds_read_u16 v46, v171 offset:528
	ds_read_u16 v47, v171 offset:1056
	ds_read_u16 v48, v171 offset:1584
	ds_read_u16 v49, v171 offset:2112
	ds_read_u16 v58, v171 offset:2640
	ds_read_u16 v59, v171 offset:3168
	ds_read_u16 v60, v170
	ds_read_u16 v61, v170 offset:32
	ds_read_u16 v62, v171
	ds_read_u16 v66, v171 offset:32
	ds_read_u16 v67, v171 offset:560
	ds_read_u16 v156, v171 offset:1088
	ds_read_u16 v68, v171 offset:1616
	ds_read_u16 v157, v171 offset:2144
	ds_read_u16 v69, v171 offset:2672
	ds_read_u16 v158, v171 offset:3200
	ds_read_u16 v54, v173 offset:144
	ds_read_u16 v55, v173 offset:288
	ds_read_u16 v56, v173 offset:432
	ds_read_u16 v63, v173 offset:576
	ds_read_u16 v57, v173 offset:720
	ds_read_u16 v64, v173 offset:864
	s_waitcnt lgkmcnt(4)
	v_perm_b32 v55, v55, v54, s74
	v_perm_b32 v65, v59, v58, s74
	s_waitcnt lgkmcnt(2)
	v_perm_b32 v56, v63, v56, s74
	ds_read_u16 v54, v172
	ds_read_u16 v159, v172 offset:32
	ds_read_u16 v63, v173
	ds_read_u16 v185, v173 offset:32
	s_waitcnt lgkmcnt(4)
	v_perm_b32 v57, v64, v57, s74
	v_perm_b32 v64, v49, v48, s74
	v_perm_b32 v62, v62, v60, s74
	s_waitcnt lgkmcnt(1)
	v_perm_b32 v54, v63, v54, s74
	v_perm_b32 v63, v47, v46, s74
	v_perm_b32 v69, v158, v69, s74
	v_perm_b32 v68, v157, v68, s74
	v_perm_b32 v67, v156, v67, s74
	v_perm_b32 v66, v66, v61, s74
	v_mfma_f32_16x16x32_bf16 v[46:49], v[62:65], v[54:57], v[94:97]
	v_add_f32_e32 v74, v74, v181
	v_cvt_pk_bf16_f32 v70, v70, v33
	v_cvt_pk_bf16_f32 v74, v74, v33
	v_mfma_f32_16x16x32_bf16 v[50:53], v[66:69], v[54:57], v[50:53]
	ds_read_u16 v54, v173 offset:176
	ds_read_u16 v55, v173 offset:320
	ds_read_u16 v56, v173 offset:464
	ds_read_u16 v57, v173 offset:608
	ds_read_u16 v58, v173 offset:752
	ds_read_u16 v59, v173 offset:896
	s_waitcnt lgkmcnt(2)
	v_perm_b32 v60, v57, v56, s74
	s_waitcnt lgkmcnt(0)
	v_perm_b32 v61, v59, v58, s74
	v_perm_b32 v59, v55, v54, s74
	v_perm_b32 v58, v185, v159, s74
	s_nop 1
	v_mfma_f32_16x16x32_bf16 v[54:57], v[62:65], v[58:61], v[82:85]
	v_mfma_f32_16x16x32_bf16 v[58:61], v[66:69], v[58:61], v[90:93]
	s_nop 1
	ds_read_u16 v82, v172 offset:64
	ds_read_u16 v90, v173 offset:64
	ds_read_u16 v83, v173 offset:208
	ds_read_u16 v91, v173 offset:352
	ds_read_u16 v84, v173 offset:496
	ds_read_u16 v92, v173 offset:640
	ds_read_u16 v85, v173 offset:784
	ds_read_u16 v93, v173 offset:928
	s_waitcnt lgkmcnt(4)
	v_perm_b32 v83, v91, v83, s74
	v_perm_b32 v82, v90, v82, s74
	s_waitcnt lgkmcnt(2)
	v_perm_b32 v84, v92, v84, s74
	s_waitcnt lgkmcnt(0)
	v_perm_b32 v85, v93, v85, s74
	s_nop 1
	v_mfma_f32_16x16x32_bf16 v[78:81], v[62:65], v[82:85], v[78:81]
	v_mfma_f32_16x16x32_bf16 v[82:85], v[66:69], v[82:85], v[86:89]
	s_nop 2
	ds_read_u16 v86, v172 offset:96
	ds_read_u16 v90, v173 offset:96
	ds_read_u16 v87, v173 offset:240
	ds_read_u16 v91, v173 offset:384
	ds_read_u16 v88, v173 offset:528
	ds_read_u16 v92, v173 offset:672
	ds_read_u16 v89, v173 offset:816
	ds_read_u16 v93, v173 offset:960
	s_waitcnt lgkmcnt(4)
	v_perm_b32 v87, v91, v87, s74
	v_perm_b32 v86, v90, v86, s74
	s_waitcnt lgkmcnt(2)
	v_perm_b32 v88, v92, v88, s74
	s_waitcnt lgkmcnt(0)
	v_perm_b32 v89, v93, v89, s74
	s_nop 1
	v_mfma_f32_16x16x32_bf16 v[62:65], v[62:65], v[86:89], v[38:41]
	v_mfma_f32_16x16x32_bf16 v[66:69], v[66:69], v[86:89], v[42:45]
	s_nop 1
	ds_read_u16 v38, v174 offset:528
	ds_read_u16 v39, v174 offset:1056
	ds_read_u16 v40, v174 offset:1584
	ds_read_u16 v41, v174 offset:2112
	ds_read_u16 v86, v174 offset:2640
	ds_read_u16 v87, v174 offset:3168
	ds_read_u16 v88, v174 offset:3696
	ds_read_u16 v89, v174
	ds_read_u16 v94, v174 offset:32
	ds_read_u16 v95, v174 offset:560
	ds_read_u16 v96, v174 offset:1088
	ds_read_u16 v97, v174 offset:1616
	ds_read_u16 v156, v174 offset:2144
	ds_read_u16 v157, v174 offset:2672
	ds_read_u16 v158, v174 offset:3200
	ds_read_u16 v159, v174 offset:3728
	ds_read_u16 v42, v175 offset:144
	ds_read_u16 v43, v175 offset:288
	ds_read_u16 v90, v175 offset:432
	ds_read_u16 v44, v175 offset:576
	ds_read_u16 v91, v175 offset:720
	ds_read_u16 v45, v175 offset:864
	ds_read_u16 v92, v175 offset:1008
	s_waitcnt lgkmcnt(4)
	v_perm_b32 v43, v90, v43, s74
	ds_read_u16 v90, v175
	ds_read_u16 v185, v175 offset:32
	s_waitcnt lgkmcnt(4)
	v_perm_b32 v44, v91, v44, s74
	v_perm_b32 v93, v88, v87, s74
	s_waitcnt lgkmcnt(2)
	v_perm_b32 v45, v92, v45, s74
	s_waitcnt lgkmcnt(1)
	v_perm_b32 v42, v42, v90, s74
	v_perm_b32 v92, v86, v41, s74
	v_perm_b32 v91, v40, v39, s74
	v_perm_b32 v90, v38, v89, s74
	v_perm_b32 v89, v159, v158, s74
	v_perm_b32 v88, v157, v156, s74
	v_perm_b32 v87, v97, v96, s74
	v_perm_b32 v86, v95, v94, s74
	v_mfma_f32_16x16x32_bf16 v[38:41], v[90:93], v[42:45], v[46:49]
	s_nop 0
	v_mfma_f32_16x16x32_bf16 v[42:45], v[86:89], v[42:45], v[50:53]
	s_nop 0
	ds_read_u16 v46, v175 offset:176
	ds_read_u16 v47, v175 offset:320
	ds_read_u16 v48, v175 offset:464
	ds_read_u16 v49, v175 offset:608
	ds_read_u16 v50, v175 offset:752
	ds_read_u16 v51, v175 offset:896
	ds_read_u16 v52, v175 offset:1040
	s_waitcnt lgkmcnt(0)
	v_perm_b32 v53, v52, v51, s74
	v_perm_b32 v52, v50, v49, s74
	v_perm_b32 v51, v48, v47, s74
	v_perm_b32 v50, v46, v185, s74
	s_nop 1
	v_mfma_f32_16x16x32_bf16 v[46:49], v[90:93], v[50:53], v[54:57]
	v_mfma_f32_16x16x32_bf16 v[54:57], v[86:89], v[50:53], v[58:61]
	ds_read_u16 v50, v175 offset:64
	ds_read_u16 v51, v175 offset:208
	ds_read_u16 v52, v175 offset:352
	ds_read_u16 v53, v175 offset:496
	ds_read_u16 v58, v175 offset:640
	ds_read_u16 v59, v175 offset:784
	ds_read_u16 v60, v175 offset:928
	ds_read_u16 v61, v175 offset:1072
	s_waitcnt lgkmcnt(0)
	v_perm_b32 v61, v61, v60, s74
	v_perm_b32 v60, v59, v58, s74
	v_perm_b32 v59, v53, v52, s74
	v_perm_b32 v58, v51, v50, s74
	s_nop 1
	v_mfma_f32_16x16x32_bf16 v[50:53], v[90:93], v[58:61], v[78:81]
	v_mfma_f32_16x16x32_bf16 v[58:61], v[86:89], v[58:61], v[82:85]
	s_nop 1
	ds_read_u16 v78, v175 offset:96
	ds_read_u16 v82, v175 offset:240
	ds_read_u16 v79, v175 offset:384
	ds_read_u16 v83, v175 offset:528
	ds_read_u16 v80, v175 offset:672
	ds_read_u16 v84, v175 offset:816
	ds_read_u16 v81, v175 offset:960
	ds_read_u16 v85, v175 offset:1104
	global_store_short v[144:145], v70, off offset:32
	v_add_f32_e32 v70, v71, v179
	global_store_short v[144:145], v74, off
	v_add_f32_e32 v74, v75, v182
	v_cvt_pk_bf16_f32 v70, v70, v33
	v_cvt_pk_bf16_f32 v74, v74, v33
	global_store_short v[146:147], v70, off offset:32
	v_add_f32_e32 v70, v72, v178
	global_store_short v[146:147], v74, off
	v_add_f32_e32 v74, v76, v183
	v_cvt_pk_bf16_f32 v70, v70, v33
	s_waitcnt lgkmcnt(0)
	v_perm_b32 v81, v85, v81, s74
	v_perm_b32 v80, v84, v80, s74
	v_perm_b32 v79, v83, v79, s74
	v_perm_b32 v78, v82, v78, s74
	v_cvt_pk_bf16_f32 v74, v74, v33
	global_store_short v[148:149], v70, off offset:32
	v_add_f32_e32 v70, v73, v177
	v_mfma_f32_16x16x32_bf16 v[62:65], v[90:93], v[78:81], v[62:65]
	global_store_short v[148:149], v74, off
	v_add_f32_e32 v74, v77, v184
	v_cvt_pk_bf16_f32 v70, v70, v33
	v_mfma_f32_16x16x32_bf16 v[66:69], v[86:89], v[78:81], v[66:69]
	v_cvt_pk_bf16_f32 v78, v42, v43
	v_cvt_pk_bf16_f32 v74, v74, v33
	global_store_short v[150:151], v74, off
	global_store_short v[150:151], v70, off offset:32
	s_waitcnt lgkmcnt(0)
	s_barrier
	v_cvt_pk_bf16_f32 v70, v38, v39
	v_cvt_pk_bf16_f32 v71, v40, v41
	v_cvt_pk_bf16_f32 v72, v46, v47
	v_cvt_pk_bf16_f32 v79, v44, v45
	ds_write2_b64 v176, v[70:71], v[78:79] offset1:4
	v_add_u32_e32 v78, 0x2000, v176
	v_cvt_pk_bf16_f32 v73, v48, v49
	v_cvt_pk_bf16_f32 v70, v54, v55
	v_cvt_pk_bf16_f32 v71, v56, v57
	ds_write2_b64 v78, v[72:73], v[70:71] offset0:32 offset1:36
	v_add_u32_e32 v72, 0x4000, v176
	v_cvt_pk_bf16_f32 v74, v50, v51
	v_cvt_pk_bf16_f32 v75, v52, v53
	v_cvt_pk_bf16_f32 v70, v58, v59
	v_cvt_pk_bf16_f32 v71, v60, v61
	ds_write2_b64 v72, v[74:75], v[70:71] offset0:64 offset1:68
	v_add_u32_e32 v72, 0x6000, v176
	v_cvt_pk_bf16_f32 v76, v62, v63
	v_cvt_pk_bf16_f32 v77, v64, v65
	v_cvt_pk_bf16_f32 v70, v66, v67
	v_cvt_pk_bf16_f32 v71, v68, v69
	ds_write2_b64 v72, v[76:77], v[70:71] offset0:96 offset1:100
	s_waitcnt lgkmcnt(0)
	s_barrier
	s_cbranch_scc1 .LBB0_444
	s_mov_b32 s34, s19
	s_branch .LBB0_434

.LBB0_564:
	v_mov_b32_e32 v1, v224
	s_lshl_b32 s17, s16, 5
	s_add_i32 s17, s17, 0xfffd0000
	v_cmp_gt_i32_e32 vcc, s75, v1
	s_and_saveexec_b64 s[8:9], vcc
	s_cbranch_execz .LBB0_577
	v_and_b32_e32 v2, 0xff, v1
	v_lshlrev_b32_e32 v32, 2, v2
	v_lshl_add_u64 v[4:5], s[42:43], 0, v[32:33]
	v_add_co_u32_e32 v4, vcc, 0x3000, v4
	v_and_b32_e32 v0, 63, v1
	s_nop 0
	v_addc_co_u32_e32 v5, vcc, 0, v5, vcc
	global_load_dword v4, v[4:5], off
	s_movk_i32 s0, 0x80
	v_cmp_gt_u32_e64 s[0:1], s0, v2
	v_lshl_add_u32 v0, v0, 1, 16
	s_mov_b64 s[10:11], 0
	v_lshlrev_b32_e32 v32, 1, v2
	v_mov_b32_e32 v5, v1
	v_lshrrev_b32_e32 v6, 2, v1
	v_and_b32_e32 v7, 3, v1
	v_add_u32_e32 v6, s17, v6
	v_lshlrev_b32_e32 v7, 7, v7
	v_add_u32_e32 v6, -1, v6
	v_mov_b64_e32 v[8:9], s[2:3]
	v_mad_i64_i32 v[8:9], s[12:13], v6, s96, v[8:9]
	v_add_co_u32_e32 v8, vcc, v7, v8
	s_nop 1
	v_addc_co_u32_e32 v9, vcc, 0, v9, vcc
	v_add_co_u32_e32 v8, vcc, 0xc403000, v8
	s_nop 1
	v_addc_co_u32_e32 v9, vcc, 0, v9, vcc
	v_cmp_gt_u32_e32 vcc, 0x88, v1
	s_and_saveexec_b64 s[12:13], vcc
	global_load_dword v10, v[8:9], off
	s_mov_b64 exec, s[12:13]
	s_waitcnt vmcnt(0)
	s_branch .LBB0_568

.LBB0_919:
	v_mov_b32_e32 v71, v224
	s_nop 0
	v_cmp_gt_i32_e32 vcc, s94, v71
	s_and_saveexec_b64 s[10:11], vcc
	s_cbranch_execz .LBB0_926
	v_and_b32_e32 v0, 0x7f, v71
	v_lshlrev_b32_e32 v32, 2, v0
	v_lshl_add_u64 v[2:3], s[42:43], 0, v[32:33]
	v_add_co_u32_e32 v2, vcc, 0x3000, v2
	s_lshl_b32 s9, s17, 5
	s_nop 0
	v_addc_co_u32_e32 v3, vcc, 0, v3, vcc
	global_load_dword v2, v[2:3], off offset:1024
	s_add_i32 s9, s9, 0xfffd0000
	v_lshl_add_u32 v3, v71, 2, 16
	s_mov_b64 s[12:13], 0
	v_lshlrev_b32_e32 v32, 1, v0
	v_mov_b32_e32 v4, v71
	v_lshrrev_b32_e32 v5, 1, v71
	v_and_b32_e32 v6, 1, v71
	v_add_u32_e32 v5, s9, v5
	v_lshlrev_b32_e32 v6, 7, v6
	v_add_u32_e32 v5, -1, v5
	v_mov_b64_e32 v[8:9], s[2:3]
	v_mad_i64_i32 v[8:9], s[14:15], v5, s96, v[8:9]
	v_add_co_u32_e32 v8, vcc, v6, v8
	s_nop 1
	v_addc_co_u32_e32 v9, vcc, 0, v9, vcc
	v_add_co_u32_e32 v8, vcc, 0x3200, v8
	s_nop 1
	v_addc_co_u32_e32 v9, vcc, 0, v9, vcc
	v_cmp_gt_u32_e32 vcc, 0x44, v71
	s_and_saveexec_b64 s[14:15], vcc
	global_load_dword v7, v[8:9], off
	s_mov_b64 exec, s[14:15]
	s_waitcnt vmcnt(0)
	s_branch .LBB0_922
